# critical-path priority: s_setprio 3 while a workgroup runs the latency-bound NSA compressed unit, back to 0 at its exit
# baseline (speedup 1.0000x reference)
; __global__ void __launch_bounds__(256, 2) mega_kernel(Params p) {
;     ...
;       for (int u = blockIdx.x; u < 512; u += G) nsa_cmp_unit(p, u, smem);
;       if (G == 512) {
;         const int qb = blockIdx.x & 31, grp = blockIdx.x >> 5;
;         int c0 = 0;
;         for (int q = 0; q < qb; ++q) c0 += ((31 - q) * 8 + 15) / 31;
;         const int n = ((31 - qb) * 8 + 15) / 31;
;         for (int k = 0; k < n; ++k) nsa_win_unit(p, 2048 + grp * 128 + c0 + k, smem);
;       }
.LBB0_372:
	s_setprio 0
	v_readlane_b32 s2, v230, 18
	v_readlane_b32 s3, v230, 19
	v_readlane_b32 s8, v229, 29
	s_and_b64 vcc, exec, s[2:3]
	v_readlane_b32 s12, v229, 33
	v_readlane_b32 s13, v229, 34
	v_readlane_b32 s9, v229, 30
	v_readlane_b32 s10, v229, 31
	v_readlane_b32 s11, v229, 32
	v_readlane_b32 s14, v229, 35
	v_readlane_b32 s15, v229, 36
	v_readlane_b32 s16, v229, 37
	v_readlane_b32 s17, v229, 38
	v_readlane_b32 s18, v229, 39
	v_readlane_b32 s19, v229, 40
	v_readlane_b32 s20, v229, 41
	v_readlane_b32 s21, v229, 42
	v_readlane_b32 s22, v229, 43
	v_readlane_b32 s23, v229, 44
	s_cbranch_vccz .LBB0_717
	s_cmp_lt_i32 s69, 1
	s_mov_b32 s1, s69
	s_cbranch_scc1 .LBB0_650
	s_cmp_eq_u32 s69, 1
	s_cbranch_scc1 .LBB0_648
	s_mov_b32 s1, 0
	v_mov_b32_e32 v0, 0x10000
	v_readlane_b32 s2, v230, 46
	s_mov_b32 s3, 0

; DI void nsa_cmp_unit(const Params& p, int u, char* smem) {
;     ...
;   const int qb = u & 31, g = (u >> 5) & 1, b = u >> 6;
;   constexpr int VSTR = 264;
;   bf16_t* Kc = (bf16_t*)smem; bf16_t* Vc = (bf16_t*)(smem + 36864);
;   __syncthreads();
;   {
;     const bf16_t* ksrc = p.kcmp + (size_t)(b * 2 + g) * 256 * 64; const bf16_t* vsrc = p.vtcmp + (size_t)(b * 2 + g) * 64 * 256;
; #pragma unroll
;     for (int q = 0; q < 8; ++q) {
;       const int idx = tid + 256 * q;
;       *(u32x4*)(Kc + (idx >> 3) * LSTR + (idx & 7) * 8) = *(const u32x4*)(ksrc + (size_t)idx * 8);
;       *(u32x4*)(Vc + (idx >> 5) * VSTR + (idx & 31) * 8) = *(const u32x4*)(vsrc + (size_t)idx * 8);
;     }
;   }
;   __syncthreads();
;   const int q0 = 128 * qb + 32 * w, tq = q0 + r; const size_t tok = (size_t)b * SEQ + tq;
.LBB0_430:
	s_setprio 3
	s_ashr_i32 s4, s1, 6
	s_bfe_u32 s10, s1, 0x10005
	s_lshl_b32 s2, s4, 1
	s_or_b32 s2, s2, s10
	s_ashr_i32 s3, s2, 31
	v_readlane_b32 s12, v230, 51
	s_lshl_b64 s[2:3], s[2:3], 15
	v_readlane_b32 s26, v229, 1
	s_waitcnt vmcnt(11)
	v_mov_b32_e32 v114, v167
	v_readlane_b32 s27, v229, 2
	s_add_u32 s8, s26, s2
	s_addc_u32 s9, s27, s3
	v_readlane_b32 s6, v229, 19
	v_ashrrev_i32_e32 v115, 31, v114
	v_readlane_b32 s7, v229, 20
	s_add_u32 s6, s6, s2
	v_lshlrev_b64 v[6:7], 4, v[114:115]
	v_add_u32_e32 v66, 0x100, v114
	v_add_u32_e32 v68, 0x200, v114
	s_addc_u32 s7, s7, s3
	v_lshl_add_u64 v[2:3], s[8:9], 0, v[6:7]
	v_ashrrev_i32_e32 v67, 31, v66
	v_ashrrev_i32_e32 v69, 31, v68
	s_barrier
	global_load_dwordx4 v[2:5], v[2:3], off
	v_lshl_add_u64 v[6:7], s[6:7], 0, v[6:7]
	v_lshlrev_b64 v[14:15], 4, v[66:67]
	v_lshlrev_b64 v[22:23], 4, v[68:69]
	global_load_dwordx4 v[6:9], v[6:7], off
	v_lshl_add_u64 v[10:11], s[8:9], 0, v[14:15]
	v_lshl_add_u64 v[18:19], s[8:9], 0, v[22:23]
	global_load_dwordx4 v[10:13], v[10:11], off
	v_lshl_add_u64 v[14:15], s[6:7], 0, v[14:15]
	global_load_dwordx4 v[18:21], v[18:19], off
	v_add_u32_e32 v70, 0x300, v114
	global_load_dwordx4 v[14:17], v[14:15], off
	v_lshl_add_u64 v[22:23], s[6:7], 0, v[22:23]
	v_ashrrev_i32_e32 v71, 31, v70
	global_load_dwordx4 v[22:25], v[22:23], off
	v_lshlrev_b64 v[30:31], 4, v[70:71]
	v_lshl_add_u64 v[26:27], s[8:9], 0, v[30:31]
	global_load_dwordx4 v[26:29], v[26:27], off
	v_add_u32_e32 v72, 0x400, v114
	v_lshl_add_u64 v[30:31], s[6:7], 0, v[30:31]
	v_ashrrev_i32_e32 v73, 31, v72
	global_load_dwordx4 v[30:33], v[30:31], off
	v_lshlrev_b64 v[38:39], 4, v[72:73]
	v_lshl_add_u64 v[34:35], s[8:9], 0, v[38:39]
	global_load_dwordx4 v[34:37], v[34:35], off
	v_add_u32_e32 v74, 0x500, v114
	v_lshl_add_u64 v[38:39], s[6:7], 0, v[38:39]
	v_ashrrev_i32_e32 v75, 31, v74
	global_load_dwordx4 v[38:41], v[38:39], off
	v_lshlrev_b64 v[46:47], 4, v[74:75]
	v_lshl_add_u64 v[42:43], s[8:9], 0, v[46:47]
	global_load_dwordx4 v[42:45], v[42:43], off
	v_add_u32_e32 v76, 0x600, v114
	v_lshl_add_u64 v[46:47], s[6:7], 0, v[46:47]
	v_ashrrev_i32_e32 v77, 31, v76
	global_load_dwordx4 v[46:49], v[46:47], off
	v_lshlrev_b64 v[54:55], 4, v[76:77]
	v_lshl_add_u64 v[50:51], s[8:9], 0, v[54:55]
	global_load_dwordx4 v[50:53], v[50:51], off
	v_add_u32_e32 v78, 0x700, v114
	v_lshl_add_u64 v[54:55], s[6:7], 0, v[54:55]
	v_ashrrev_i32_e32 v79, 31, v78
	global_load_dwordx4 v[54:57], v[54:55], off
	v_lshlrev_b64 v[62:63], 4, v[78:79]
	v_lshl_add_u64 v[58:59], s[8:9], 0, v[62:63]
	global_load_dwordx4 v[58:61], v[58:59], off
	v_lshl_add_u64 v[62:63], s[6:7], 0, v[62:63]
	global_load_dwordx4 v[62:65], v[62:63], off
	v_lshlrev_b32_e32 v0, 4, v114
	v_and_b32_e32 v71, 0x70, v0
	v_lshrrev_b32_e32 v67, 3, v114
	v_and_b32_e32 v73, 0x1f0, v0
	v_add_u32_e32 v0, 0, v71
	s_movk_i32 s8, 0x90
	v_ashrrev_i32_e32 v69, 5, v114
	v_lshrrev_b32_e32 v75, 3, v66
	v_ashrrev_i32_e32 v77, 5, v66
	v_add_u32_e32 v66, 0, v73
	v_mad_u64_u32 v[80:81], s[6:7], v67, s8, v[0:1]
	s_movk_i32 s9, 0x210
	s_waitcnt vmcnt(26)
	v_mad_u64_u32 v[82:83], s[6:7], v69, s9, v[66:67]
	v_mad_u64_u32 v[84:85], s[6:7], v75, s8, v[0:1]
	v_mad_u64_u32 v[86:87], s[6:7], v77, s9, v[66:67]
	s_waitcnt vmcnt(15)
	ds_write_b128 v80, v[2:5]
	s_waitcnt vmcnt(14)
	ds_write_b128 v82, v[6:9] offset:36864
	s_waitcnt vmcnt(13)
	ds_write_b128 v84, v[10:13]
	s_waitcnt vmcnt(11)
	ds_write_b128 v86, v[14:17] offset:36864
	v_lshrrev_b32_e32 v2, 3, v68
	v_mad_u64_u32 v[2:3], s[6:7], v2, s8, v[0:1]
	ds_write_b128 v2, v[18:21]
	v_ashrrev_i32_e32 v2, 5, v68
	v_mad_u64_u32 v[2:3], s[6:7], v2, s9, v[66:67]
	s_waitcnt vmcnt(10)
	ds_write_b128 v2, v[22:25] offset:36864
	v_lshrrev_b32_e32 v2, 3, v70
	v_mad_u64_u32 v[2:3], s[6:7], v2, s8, v[0:1]
	s_waitcnt vmcnt(9)
	ds_write_b128 v2, v[26:29]
	v_ashrrev_i32_e32 v2, 5, v70
	v_mad_u64_u32 v[2:3], s[6:7], v2, s9, v[66:67]
	s_waitcnt vmcnt(8)
	ds_write_b128 v2, v[30:33] offset:36864
	v_lshrrev_b32_e32 v2, 3, v72
	v_mad_u64_u32 v[2:3], s[6:7], v2, s8, v[0:1]
	s_waitcnt vmcnt(7)
	ds_write_b128 v2, v[34:37]
	v_ashrrev_i32_e32 v2, 5, v72
	v_mad_u64_u32 v[2:3], s[6:7], v2, s9, v[66:67]
	s_waitcnt vmcnt(6)
	ds_write_b128 v2, v[38:41] offset:36864
	v_lshrrev_b32_e32 v2, 3, v74
	v_mad_u64_u32 v[2:3], s[6:7], v2, s8, v[0:1]
	s_waitcnt vmcnt(5)
	ds_write_b128 v2, v[42:45]
	v_ashrrev_i32_e32 v2, 5, v74
	v_mad_u64_u32 v[2:3], s[6:7], v2, s9, v[66:67]
	s_waitcnt vmcnt(4)
	ds_write_b128 v2, v[46:49] offset:36864
	v_lshrrev_b32_e32 v2, 3, v76
	v_mad_u64_u32 v[2:3], s[6:7], v2, s8, v[0:1]
	s_waitcnt vmcnt(3)
	ds_write_b128 v2, v[50:53]
	v_ashrrev_i32_e32 v2, 5, v76
	v_mad_u64_u32 v[2:3], s[6:7], v2, s9, v[66:67]
	s_waitcnt vmcnt(2)
	ds_write_b128 v2, v[54:57] offset:36864
	v_lshrrev_b32_e32 v2, 3, v78
	v_mad_u64_u32 v[2:3], s[6:7], v2, s8, v[0:1]
	v_ashrrev_i32_e32 v0, 5, v78
	v_readfirstlane_b32 s5, v114
	s_waitcnt vmcnt(1)
	ds_write_b128 v2, v[58:61]
	v_mad_u64_u32 v[2:3], s[6:7], v0, s9, v[66:67]
	s_lshl_b32 s6, s1, 7
	s_ashr_i32 s29, s5, 1
	s_and_b32 s28, s6, 0xf80
	s_andn2_b32 s29, s29, 31
	v_and_b32_e32 v124, 31, v114
	s_add_i32 s6, s29, s28
	s_waitcnt vmcnt(0)
	ds_write_b128 v2, v[62:65] offset:36864
	v_or_b32_e32 v2, s6, v124
	v_ashrrev_i32_e32 v3, 31, v2
	s_ashr_i32 s5, s4, 31
	v_readlane_b32 s13, v230, 52
	v_readlane_b32 s14, v230, 53
	v_readlane_b32 s15, v230, 54
	v_readlane_b32 s16, v230, 55
	v_readlane_b32 s17, v230, 56
	v_readlane_b32 s18, v230, 57
	v_readlane_b32 s19, v230, 58
	v_readlane_b32 s20, v230, 59
	v_readlane_b32 s21, v230, 60
	v_readlane_b32 s22, v230, 61
	v_readlane_b32 s23, v230, 62
	v_readlane_b32 s24, v230, 63
	v_readlane_b32 s25, v229, 0
	s_lshl_b64 s[4:5], s[4:5], 22
	v_lshlrev_b64 v[4:5], 10, v[2:3]
	v_lshl_add_u64 v[4:5], v[4:5], 0, s[4:5]
	v_readlane_b32 s12, v229, 29
	v_lshlrev_b64 v[4:5], 1, v[4:5]
	v_readlane_b32 s24, v229, 41
	v_readlane_b32 s25, v229, 42
	s_lshl_b32 s58, s10, 10
	v_lshlrev_b32_e32 v0, 1, v166
	v_lshl_add_u64 v[6:7], s[24:25], 0, v[4:5]
	v_lshl_add_u64 v[8:9], v[6:7], 0, s[58:59]
	v_lshl_add_u64 v[8:9], v[8:9], 0, v[0:1]
	s_waitcnt lgkmcnt(0)
	s_barrier
; DI void nsa_cmp_unit(const Params& p, int u, char* smem) {
;     ...
;   const int q0 = 128 * qb + 32 * w, tq = q0 + r; const size_t tok = (size_t)b * SEQ + tq;
;   const int nc = tq >= 31 ? ((tq - 31) >> 4) + 1 : 0;
;   const int ncw = (q0 >> 4) + 1; int ntile = (ncw + 31) >> 5; ntile = ntile > 8 ? 8 : ntile;
;   f32x16 imp[2];
; #pragma unroll
;   for (int jt = 0; jt < 2; ++jt)
; #pragma unroll
;     for (int i = 0; i < 16; ++i) imp[jt][i] = 0.f;
;   bf16x8 qn[4]; load_q(p.Q + tok * 1024 + (8 * g) * 64, qn);
; #pragma unroll 1
;   for (int hd = 0; hd < 8; ++hd) {
;     const int head = 8 * g + hd;
;     bf16x8 qf[4];
; #pragma unroll
;     for (int ks = 0; ks < 4; ++ks) qf[ks] = qn[ks];
;     if (hd + 1 < 8) load_q(p.Q + tok * 1024 + (head + 1) * 64, qn);
	global_load_dwordx4 v[98:101], v[8:9], off offset:32
	global_load_dwordx4 v[102:105], v[8:9], off
	global_load_dwordx4 v[106:109], v[8:9], off offset:64
	global_load_dwordx4 v[110:113], v[8:9], off offset:96
	v_subrev_u32_e32 v3, 31, v2
	v_ashrrev_i32_e32 v3, 4, v3
	v_add_u32_e32 v3, 1, v3
	v_cmp_lt_i32_e32 vcc, 30, v2
	s_ashr_i32 s4, s6, 4
	s_add_i32 s4, s4, 32
	v_cndmask_b32_e32 v116, 0, v3, vcc
	v_and_b32_e32 v3, 64, v202
	v_xor_b32_e32 v2, 32, v202
	v_add_u32_e32 v3, 64, v3
	s_ashr_i32 s4, s4, 5
	v_cmp_lt_i32_e32 vcc, v2, v3
	v_bfe_u32 v8, v114, 5, 1
	s_min_i32 s31, s4, 8
	s_lshl_b32 s54, s10, 3
	v_cndmask_b32_e32 v2, v202, v2, vcc
	s_cmp_gt_i32 s4, 0
	v_lshlrev_b32_e32 v126, 2, v2
	v_lshlrev_b32_e32 v125, 4, v8
	v_mul_u32_u24_e32 v2, 0x210, v124
	v_lshl_add_u64 v[120:121], v[6:7], 0, v[0:1]
	v_mul_u32_u24_e32 v0, 0x90, v124
	s_cselect_b64 s[4:5], -1, 0
	v_add3_u32 v128, v0, v125, 0
	v_lshl_or_b32 v0, v8, 3, v2
	s_add_i32 s6, 0, 0x9000
	v_mov_b32_e32 v14, v1
	v_mov_b32_e32 v15, v1
	v_lshlrev_b32_e32 v127, 2, v8
	v_lshl_add_u64 v[118:119], v[178:179], 0, v[4:5]
	v_add_u32_e32 v130, s6, v0
	v_mov_b32_e32 v0, v1
	v_mov_b32_e32 v2, v1
	v_mov_b32_e32 v3, v1
	v_mov_b32_e32 v4, v1
	v_mov_b32_e32 v5, v1
	v_mov_b32_e32 v6, v1
	v_mov_b32_e32 v7, v1
	v_mov_b32_e32 v8, v1
	v_mov_b32_e32 v9, v1
	v_mov_b32_e32 v10, v1
	v_mov_b32_e32 v11, v1
	v_mov_b32_e32 v12, v1
	v_mov_b32_e32 v13, v1
	v_mov_b64_e32 v[32:33], v[14:15]
	v_lshlrev_b32_e32 v131, 2, v124
	v_mov_b64_e32 v[30:31], v[12:13]
	v_mov_b64_e32 v[28:29], v[10:11]
	v_mov_b64_e32 v[26:27], v[8:9]
	v_mov_b64_e32 v[24:25], v[6:7]
	v_mov_b64_e32 v[22:23], v[4:5]
	v_mov_b64_e32 v[20:21], v[2:3]
	v_mov_b64_e32 v[18:19], v[0:1]
	v_mov_b64_e32 v[16:17], v[14:15]
	s_mov_b32 s30, 0
	v_mov_b32_e32 v115, v116
	v_or_b32_e32 v129, 27, v127
	v_sub_u32_e32 v132, 0, v131
	v_add_u32_e32 v133, -8, v131
	v_add_u32_e32 v134, 0x78, v131
	v_or_b32_e32 v135, 0x80, v131
	v_subrev_u32_e32 v136, 24, v131
	v_add_u32_e32 v137, -16, v131
	v_add_u32_e32 v138, 0x68, v131
	v_add_u32_e32 v139, 0x70, v131
	v_mov_b64_e32 v[14:15], v[12:13]
	v_mov_b64_e32 v[12:13], v[10:11]
	v_mov_b64_e32 v[10:11], v[8:9]
	v_mov_b64_e32 v[8:9], v[6:7]
	v_mov_b64_e32 v[6:7], v[4:5]
	v_mov_b64_e32 v[4:5], v[2:3]
	v_mov_b64_e32 v[2:3], v[0:1]
	v_readlane_b32 s13, v229, 30
	v_readlane_b32 s14, v229, 31
	v_readlane_b32 s15, v229, 32
	v_readlane_b32 s16, v229, 33
	s_waitcnt vmcnt(3)
	v_mov_b64_e32 v[82:83], v[98:99]
	s_waitcnt vmcnt(2)
	v_mov_b64_e32 v[86:87], v[102:103]
	s_waitcnt vmcnt(1)
	v_mov_b64_e32 v[90:91], v[106:107]
	s_waitcnt vmcnt(0)
	v_mov_b64_e32 v[94:95], v[110:111]
	v_mov_b64_e32 v[84:85], v[100:101]
	v_mov_b64_e32 v[88:89], v[104:105]
	v_mov_b64_e32 v[92:93], v[108:109]
	v_mov_b64_e32 v[96:97], v[112:113]
	v_readlane_b32 s17, v229, 34
	v_readlane_b32 s18, v229, 35
	v_readlane_b32 s19, v229, 36
	v_readlane_b32 s20, v229, 37
	v_readlane_b32 s21, v229, 38
	v_readlane_b32 s22, v229, 39
	v_readlane_b32 s23, v229, 40
	v_readlane_b32 s26, v229, 43
	v_readlane_b32 s27, v229, 44
	s_add_i32 s55, s30, s54
	s_cmp_eq_u32 s30, 7
	s_cbranch_scc1 .LBB0_433
	s_branch .LBB0_432
